# dil_tile<1> P*V: 20 V fragment loads issued together (were ~10 serial load/wait/MFMA round trips per tile); pool/conv loop-top drain removed
# speedup vs baseline: 1.0165x; 1.0037x over previous
.LBB0_41:
	s_nop 1
	v_add_u32_e32 v2, s16, v114
	s_mov_b64 s[0:1], -1
	v_readfirstlane_b32 s2, v2
	s_cmp_gt_i32 s2, 11
	s_cbranch_scc0 .LBB0_47
	v_lshl_add_u32 v2, s2, 6, v115
	s_mov_b32 s0, 0xaaaaaaab
	v_mul_hi_u32 v3, v2, s0
	v_lshrrev_b32_e32 v3, 5, v3
	s_movk_i32 s0, 0xffd0
	v_mul_lo_u32 v4, v3, s0
	v_lshl_add_u32 v74, v3, 2, s15
	v_and_b32_e32 v3, 0xffc, v74
	v_add_lshl_u32 v2, v4, v2, 3
	v_mov_b32_e32 v10, 0
	v_cmp_ne_u32_e32 vcc, 0, v3
	v_ashrrev_i32_e32 v3, 31, v2
	v_mov_b32_e32 v34, 0
	v_mov_b32_e32 v35, 0
	v_mov_b32_e32 v36, 0
	v_mov_b32_e32 v37, 0
	v_mov_b32_e32 v30, 0
	v_mov_b32_e32 v31, 0
	v_mov_b32_e32 v32, 0
	v_mov_b32_e32 v33, 0
	s_and_saveexec_b64 s[0:1], vcc
	s_cbranch_execz .LBB0_44
	v_add_u32_e32 v6, -2, v74
	v_mov_b64_e32 v[4:5], s[4:5]
	v_mad_i64_i32 v[4:5], s[18:19], v6, s17, v[4:5]
	v_lshl_add_u64 v[4:5], v[2:3], 1, v[4:5]
	flat_load_dwordx4 v[34:37], v[4:5] offset:768
	flat_load_dwordx4 v[30:33], v[4:5] offset:2304

.LBB0_178:
	v_or_b32_e32 v2, s47, v147
	v_ashrrev_i32_e32 v3, 31, v2
	v_lshlrev_b64 v[4:5], 8, v[2:3]
	v_lshl_add_u64 v[12:13], v[4:5], 0, s[14:15]
	v_add_u32_e32 v15, v2, v82
	v_lshlrev_b64 v[4:5], 7, v[12:13]
	v_subrev_u32_e32 v3, s44, v15
	v_lshl_add_u64 v[10:11], s[40:41], 0, v[4:5]
	v_add_u32_e32 v18, s9, v3
	v_lshlrev_b32_e32 v8, 1, v134
	v_mov_b32_e32 v9, v1
	v_lshl_add_u64 v[4:5], v[40:41], 1, v[10:11]
	v_ashrrev_i32_e32 v19, 31, v18
	v_lshl_add_u64 v[4:5], v[4:5], 0, v[8:9]
	v_lshlrev_b64 v[18:19], 11, v[18:19]
	v_add_co_u32_e32 v4, vcc, s8, v4
	v_lshl_add_u64 v[6:7], v[42:43], 1, v[10:11]
	v_lshl_add_u64 v[18:19], s[50:51], 0, v[18:19]
	v_addc_co_u32_e32 v5, vcc, 0, v5, vcc
	v_lshl_add_u64 v[6:7], v[6:7], 0, v[8:9]
	v_lshlrev_b32_e32 v16, 1, v136
	v_mov_b32_e32 v17, v1
	v_lshl_add_u64 v[18:19], s[12:13], 1, v[18:19]
	v_lshl_add_u32 v14, v3, 2, 0
	v_or_b32_e32 v12, s46, v12
	v_add_co_u32_e32 v6, vcc, s8, v6
	v_lshl_add_u64 v[56:57], v[18:19], 0, v[16:17]
	v_add_u32_e32 v16, 0x11000, v14
	v_lshlrev_b64 v[12:13], 7, v[12:13]
	v_lshl_add_u64 v[20:21], v[10:11], 0, v[0:1]
	v_lshl_add_u64 v[22:23], v[26:27], 1, v[10:11]
	v_lshl_add_u64 v[24:25], v[28:29], 1, v[10:11]
	v_lshl_add_u64 v[60:61], v[30:31], 1, v[10:11]
	v_lshl_add_u64 v[62:63], v[32:33], 1, v[10:11]
	v_lshl_add_u64 v[64:65], v[34:35], 1, v[10:11]
	v_lshl_add_u64 v[66:67], v[36:37], 1, v[10:11]
	v_lshl_add_u64 v[68:69], v[38:39], 1, v[10:11]
	v_addc_co_u32_e32 v7, vcc, 0, v7, vcc
	ds_read_b32 v58, v16
	v_lshl_add_u64 v[16:17], v[144:145], 0, v[12:13]
	v_lshl_add_u64 v[104:105], v[20:21], 0, v[8:9]
	v_lshl_add_u64 v[106:107], v[22:23], 0, v[8:9]
	v_lshl_add_u64 v[24:25], v[24:25], 0, v[8:9]
	v_lshl_add_u64 v[108:109], v[60:61], 0, v[8:9]
	v_lshl_add_u64 v[110:111], v[62:63], 0, v[8:9]
	v_lshl_add_u64 v[112:113], v[64:65], 0, v[8:9]
	v_lshl_add_u64 v[114:115], v[66:67], 0, v[8:9]
	v_lshl_add_u64 v[116:117], v[68:69], 0, v[8:9]
	flat_load_dwordx4 v[10:13], v[16:17]
	s_nop 0
	flat_load_dwordx4 v[16:19], v[16:17] offset:64
	v_add_co_u32_e32 v54, vcc, s49, v56
	flat_load_dwordx4 v[20:23], v[104:105]
	flat_load_dwordx4 v[64:67], v[24:25]
	flat_load_dwordx4 v[60:63], v[106:107]
	flat_load_dwordx4 v[68:71], v[108:109]
	flat_load_dwordx4 v[72:75], v[110:111]
	flat_load_dwordx4 v[84:87], v[112:113]
	flat_load_dwordx4 v[88:91], v[114:115]
	flat_load_dwordx4 v[92:95], v[116:117]
	flat_load_dwordx4 v[96:99], v[4:5]
	flat_load_dwordx4 v[100:103], v[6:7] offset:512
	v_addc_co_u32_e32 v55, vcc, 0, v57, vcc
	v_readlane_b32 vcc_lo, v253, 37
	v_readlane_b32 vcc_hi, v253, 38
	s_mov_b32 s47, 0xff800000
	v_add_u32_e32 v14, 0x11400, v14
	v_lshlrev_b32_e32 v2, 8, v2
	s_waitcnt vmcnt(0) lgkmcnt(0)
	v_mfma_f32_16x16x32_bf16 v[20:23], v[20:23], v[10:13], 0
	v_mfma_f32_16x16x32_bf16 v[60:63], v[60:63], v[10:13], 0
	v_mfma_f32_16x16x32_bf16 v[64:67], v[64:67], v[10:13], 0
	v_mfma_f32_16x16x32_bf16 v[68:71], v[68:71], v[10:13], 0
	v_mfma_f32_16x16x32_bf16 v[72:75], v[72:75], v[10:13], 0
	v_mfma_f32_16x16x32_bf16 v[84:87], v[84:87], v[10:13], 0
	v_mfma_f32_16x16x32_bf16 v[88:91], v[88:91], v[10:13], 0
	v_mfma_f32_16x16x32_bf16 v[92:95], v[92:95], v[10:13], 0
	v_mfma_f32_16x16x32_bf16 v[96:99], v[96:99], v[10:13], 0
	v_mfma_f32_16x16x32_bf16 v[8:11], v[100:103], v[10:13], 0
	flat_load_dwordx4 v[100:103], v[104:105] offset:64
	v_max_f32_e32 v12, v58, v58
	s_waitcnt vmcnt(0) lgkmcnt(0)
	v_mfma_f32_16x16x32_bf16 v[20:23], v[100:103], v[16:19], v[20:23]
	flat_load_dwordx4 v[100:103], v[106:107] offset:64
	ds_read_b32 v106, v14
	s_waitcnt vmcnt(0) lgkmcnt(0)
	v_mfma_f32_16x16x32_bf16 v[60:63], v[100:103], v[16:19], v[60:63]
	flat_load_dwordx4 v[100:103], v[24:25] offset:64
	s_nop 6
	v_cndmask_b32_e64 v13, v227, v60, s[34:35]
	s_waitcnt vmcnt(0) lgkmcnt(0)
	v_mfma_f32_16x16x32_bf16 v[64:67], v[100:103], v[16:19], v[64:67]
	flat_load_dwordx4 v[100:103], v[108:109] offset:64
	s_waitcnt vmcnt(0) lgkmcnt(0)
	v_mfma_f32_16x16x32_bf16 v[68:71], v[100:103], v[16:19], v[68:71]
	flat_load_dwordx4 v[100:103], v[110:111] offset:64
	s_nop 6
	v_cndmask_b32_e64 v24, v227, v69, s[66:67]
	s_waitcnt vmcnt(0) lgkmcnt(0)
	v_mfma_f32_16x16x32_bf16 v[72:75], v[100:103], v[16:19], v[72:75]
	flat_load_dwordx4 v[100:103], v[112:113] offset:64
	v_cndmask_b32_e64 v25, v227, v70, s[68:69]
	s_nop 5
	v_cndmask_b32_e64 v69, v227, v72, s[72:73]
	s_waitcnt vmcnt(0) lgkmcnt(0)
	v_mfma_f32_16x16x32_bf16 v[84:87], v[100:103], v[16:19], v[84:87]
	flat_load_dwordx4 v[100:103], v[114:115] offset:64
	v_cndmask_b32_e64 v83, v227, v73, s[74:75]
	v_cndmask_b32_e64 v74, v227, v74, s[76:77]
	s_waitcnt vmcnt(0) lgkmcnt(0)
	v_mfma_f32_16x16x32_bf16 v[88:91], v[100:103], v[16:19], v[88:91]
	flat_load_dwordx4 v[100:103], v[116:117] offset:64
	v_cndmask_b32_e64 v75, v227, v75, s[78:79]
	s_nop 0
	v_cndmask_b32_e64 v84, v227, v84, s[80:81]
	s_waitcnt vmcnt(0) lgkmcnt(0)
	v_mfma_f32_16x16x32_bf16 v[92:95], v[100:103], v[16:19], v[92:95]
	flat_load_dwordx4 v[100:103], v[4:5] offset:64
	v_cndmask_b32_e64 v85, v227, v85, s[82:83]
	flat_load_dwordx4 v[4:7], v[6:7] offset:576
	s_waitcnt vmcnt(0) lgkmcnt(0)
	v_mfma_f32_16x16x32_bf16 v[4:7], v[4:7], v[16:19], v[8:11]
	s_nop 2
	v_cndmask_b32_e32 v8, v227, v20, vcc
	v_cndmask_b32_e64 v9, v227, v21, s[26:27]
	v_cndmask_b32_e64 v10, v227, v22, s[28:29]
	v_cndmask_b32_e64 v11, v227, v23, s[30:31]
	v_max3_f32 v60, v8, s47, v9
	v_mfma_f32_16x16x32_bf16 v[96:99], v[100:103], v[16:19], v[96:99]
	v_cndmask_b32_e64 v16, v227, v61, s[36:37]
	v_max3_f32 v60, v60, v10, v11
	v_cndmask_b32_e64 v17, v227, v62, s[0:1]
	v_cndmask_b32_e64 v18, v227, v63, s[54:55]
	v_max3_f32 v60, v60, v13, v16
	v_cndmask_b32_e64 v19, v227, v64, s[56:57]
	v_cndmask_b32_e64 v20, v227, v65, s[58:59]
	v_max3_f32 v60, v60, v17, v18
	v_cndmask_b32_e64 v21, v227, v66, s[60:61]
	v_cndmask_b32_e64 v22, v227, v67, s[62:63]
	v_max3_f32 v60, v60, v19, v20
	v_cndmask_b32_e64 v23, v227, v68, s[64:65]
	v_max3_f32 v60, v60, v21, v22
	v_cndmask_b32_e64 v68, v227, v71, s[70:71]
	v_max3_f32 v60, v60, v23, v24
	v_max3_f32 v60, v60, v25, v68
	v_max3_f32 v60, v60, v69, v83
	v_max3_f32 v60, v60, v74, v75
	v_cndmask_b32_e64 v86, v227, v86, s[84:85]
	v_cndmask_b32_e64 v87, v227, v87, s[86:87]
	v_max3_f32 v60, v60, v84, v85
	v_cndmask_b32_e64 v88, v227, v88, s[88:89]
	v_cndmask_b32_e64 v89, v227, v89, s[90:91]
	v_max3_f32 v60, v60, v86, v87
	v_cndmask_b32_e64 v90, v227, v90, s[92:93]
	v_cndmask_b32_e64 v91, v227, v91, s[94:95]
	v_max3_f32 v60, v60, v88, v89
	v_cndmask_b32_e64 v92, v227, v92, s[96:97]
	v_cndmask_b32_e64 v93, v227, v93, s[38:39]
	v_max3_f32 v60, v60, v90, v91
	v_cndmask_b32_e64 v94, v227, v94, s[4:5]
	v_cndmask_b32_e64 v95, v227, v95, s[6:7]
	v_max3_f32 v60, v60, v92, v93
	v_cndmask_b32_e64 v96, v96, v227, s[16:17]
	v_cndmask_b32_e64 v97, v97, v227, s[18:19]
	v_max3_f32 v60, v60, v94, v95
	v_cndmask_b32_e64 v98, v98, v227, s[20:21]
	v_cndmask_b32_e64 v99, v99, v227, s[22:23]
	v_max3_f32 v60, v60, v96, v97
	v_cndmask_b32_e64 v4, v4, v227, s[52:53]
	v_cndmask_b32_e64 v5, v5, v227, s[10:11]
	v_max3_f32 v60, v60, v98, v99
	v_cndmask_b32_e64 v6, v6, v227, s[42:43]
	v_cndmask_b32_e64 v7, v7, v227, s[24:25]
	v_max3_f32 v60, v60, v4, v5
	v_max3_f32 v60, v60, v6, v7
	ds_bpermute_b32 v61, v80, v60
	s_movk_i32 s47, 0x110
	v_mul_lo_u32 v3, v3, s47
	v_add_u32_e32 v3, 0, v3
	s_mov_b32 s47, 1
	s_waitcnt lgkmcnt(0)
	v_max_f32_e32 v61, v61, v61
	v_max_f32_e32 v60, v60, v61
	ds_bpermute_b32 v61, v81, v60
	s_waitcnt lgkmcnt(0)
	v_max_f32_e32 v61, v61, v61
	v_max_f32_e32 v100, v60, v61
	v_max_f32_e32 v12, v12, v100
	v_sub_f32_e32 v58, v58, v12
	v_sub_f32_e32 v109, v100, v12
	v_lshrrev_b32_e32 v12, 2, v15
	v_add_u32_e32 v12, v12, v136
	v_bitop3_b32 v61, v12, 32, 60 bitop3:0x6c
	v_and_b32_e32 v15, 60, v12
	v_add_u32_e32 v60, 16, v12
	v_add_u32_e32 v12, 48, v12
	v_lshl_add_u32 v64, v61, 2, v3
	v_and_b32_e32 v12, 60, v12
	ds_read_b128 v[64:67], v64
	v_lshl_add_u32 v14, v15, 2, v3
	v_and_b32_e32 v15, 60, v60
	ds_read_b128 v[60:63], v14
	v_lshl_add_u32 v14, v15, 2, v3
	v_lshl_add_u32 v3, v12, 2, v3
	ds_read_b128 v[70:73], v14
	ds_read_b128 v[102:105], v3
	v_sub_f32_e32 v3, v8, v100
	v_sub_f32_e32 v8, v9, v100
	v_sub_f32_e32 v117, v94, v100
	v_exp_f32_e32 v94, v3
	v_sub_f32_e32 v9, v10, v100
	v_sub_f32_e32 v118, v95, v100
	v_exp_f32_e32 v95, v8
	v_sub_f32_e32 v10, v11, v100
	v_sub_f32_e32 v119, v96, v100
	v_exp_f32_e32 v96, v9
	v_sub_f32_e32 v11, v13, v100
	v_sub_f32_e32 v15, v19, v100
	v_sub_f32_e32 v19, v23, v100
	v_sub_f32_e32 v23, v69, v100
	v_sub_f32_e32 v69, v84, v100
	v_sub_f32_e32 v120, v97, v100
	v_exp_f32_e32 v97, v10
	v_sub_f32_e32 v12, v16, v100
	v_sub_f32_e32 v113, v90, v100
	v_sub_f32_e32 v121, v98, v100
	v_exp_f32_e32 v98, v11
	v_exp_f32_e32 v90, v19
	v_exp_f32_e32 v19, v23
	v_exp_f32_e32 v23, v69
	v_add_f32_e32 v69, 0, v94
	v_sub_f32_e32 v13, v17, v100
	v_sub_f32_e32 v122, v99, v100
	v_exp_f32_e32 v99, v12
	v_add_f32_e32 v69, v95, v69
	v_sub_f32_e32 v14, v18, v100
	v_sub_f32_e32 v16, v20, v100
	v_sub_f32_e32 v17, v21, v100
	v_sub_f32_e32 v18, v22, v100
	v_sub_f32_e32 v20, v24, v100
	v_sub_f32_e32 v21, v25, v100
	v_sub_f32_e32 v22, v68, v100
	v_sub_f32_e32 v24, v83, v100
	v_sub_f32_e32 v25, v74, v100
	v_sub_f32_e32 v68, v75, v100
	v_sub_f32_e32 v74, v85, v100
	v_sub_f32_e32 v75, v86, v100
	v_sub_f32_e32 v83, v87, v100
	v_sub_f32_e32 v84, v88, v100
	v_sub_f32_e32 v112, v89, v100
	v_sub_f32_e32 v114, v91, v100
	v_sub_f32_e32 v115, v92, v100
	v_sub_f32_e32 v116, v93, v100
	v_sub_f32_e32 v123, v4, v100
	v_sub_f32_e32 v124, v5, v100
	v_sub_f32_e32 v125, v6, v100
	v_sub_f32_e32 v126, v7, v100
	v_exp_f32_e32 v100, v13
	v_add_f32_e32 v69, v96, v69
	v_exp_f32_e32 v101, v14
	v_add_f32_e32 v69, v97, v69
	v_exp_f32_e32 v86, v15
	v_add_f32_e32 v69, v98, v69
	v_exp_f32_e32 v88, v16
	v_exp_f32_e32 v85, v83
	v_add_f32_e32 v83, v99, v69
	v_exp_f32_e32 v87, v17
	v_add_f32_e32 v83, v100, v83
	v_exp_f32_e32 v89, v18
	v_add_f32_e32 v83, v101, v83
	v_add_f32_e32 v83, v86, v83
	v_exp_f32_e32 v91, v20
	v_add_f32_e32 v83, v88, v83
	v_exp_f32_e32 v92, v21
	v_add_f32_e32 v83, v87, v83
	v_exp_f32_e32 v93, v22
	v_add_f32_e32 v83, v89, v83
	v_add_f32_e32 v83, v90, v83
	v_exp_f32_e32 v21, v24
	v_add_f32_e32 v83, v91, v83
	v_exp_f32_e32 v20, v25
	v_add_f32_e32 v83, v92, v83
	v_exp_f32_e32 v22, v68
	v_add_f32_e32 v83, v93, v83
	v_add_f32_e32 v83, v19, v83
	v_exp_f32_e32 v24, v74
	v_add_f32_e32 v83, v21, v83
	v_exp_f32_e32 v25, v75
	v_add_f32_e32 v83, v20, v83
	v_add_f32_e32 v83, v22, v83
	v_exp_f32_e32 v6, v84
	v_add_f32_e32 v83, v23, v83
	v_exp_f32_e32 v8, v112
	v_add_f32_e32 v83, v24, v83
	v_exp_f32_e32 v7, v113
	v_add_f32_e32 v83, v25, v83
	v_exp_f32_e32 v9, v114
	v_add_f32_e32 v83, v85, v83
	v_exp_f32_e32 v15, v115
	v_add_f32_e32 v83, v6, v83
	v_exp_f32_e32 v16, v116
	v_add_f32_e32 v83, v8, v83
	v_exp_f32_e32 v17, v117
	v_add_f32_e32 v83, v7, v83
	v_exp_f32_e32 v18, v118
	v_add_f32_e32 v83, v9, v83
	v_exp_f32_e32 v3, v119
	v_add_f32_e32 v83, v15, v83
	v_exp_f32_e32 v5, v120
	v_add_f32_e32 v83, v16, v83
	v_exp_f32_e32 v4, v121
	v_add_f32_e32 v83, v17, v83
	v_exp_f32_e32 v10, v122
	v_add_f32_e32 v83, v18, v83
	v_exp_f32_e32 v11, v123
	v_add_f32_e32 v83, v3, v83
	v_exp_f32_e32 v12, v124
	v_add_f32_e32 v83, v5, v83
	v_exp_f32_e32 v13, v125
	v_add_f32_e32 v83, v4, v83
	v_exp_f32_e32 v14, v126
	v_add_f32_e32 v83, v10, v83
	v_add_f32_e32 v83, v11, v83
	v_add_f32_e32 v83, v12, v83
	v_add_f32_e32 v83, v13, v83
	v_add_f32_e32 v83, v14, v83
	ds_bpermute_b32 v84, v80, v83
	v_cmp_gt_f32_e32 vcc, s48, v58
	v_cvt_pk_bf16_f32 v94, v94, v95
	v_cvt_pk_bf16_f32 v95, v96, v97
	v_cvt_pk_bf16_f32 v96, v98, v99
	s_waitcnt lgkmcnt(0)
	v_add_f32_e32 v83, v83, v84
	ds_bpermute_b32 v84, v81, v83
	v_cndmask_b32_e32 v107, 0, v225, vcc
	v_cndmask_b32_e32 v108, 0, v226, vcc
	v_cmp_gt_f32_e32 vcc, s48, v109
	v_add_f32_e32 v58, v58, v107
	v_exp_f32_e32 v58, v58
	v_cndmask_b32_e32 v110, 0, v225, vcc
	v_add_f32_e32 v68, v109, v110
	v_exp_f32_e32 v68, v68
	v_cndmask_b32_e32 v111, 0, v226, vcc
	v_ldexp_f32 v108, v58, v108
	v_pk_mul_f32 v[60:61], v[60:61], v[108:109] op_sel_hi:[1,0]
	v_ldexp_f32 v58, v68, v111
	v_pk_mul_f32 v[68:69], v[62:63], v[108:109] op_sel_hi:[1,0]
	v_pk_mul_f32 v[62:63], v[70:71], v[108:109] op_sel_hi:[1,0]
	v_pk_mul_f32 v[70:71], v[72:73], v[108:109] op_sel_hi:[1,0]
	v_pk_mul_f32 v[64:65], v[64:65], v[108:109] op_sel_hi:[1,0]
	v_pk_mul_f32 v[72:73], v[66:67], v[108:109] op_sel_hi:[1,0]
	v_pk_mul_f32 v[66:67], v[108:109], v[102:103] op_sel_hi:[0,1]
	v_pk_mul_f32 v[74:75], v[108:109], v[104:105] op_sel_hi:[0,1]
	v_mov_b32_e32 v109, v58
	s_waitcnt lgkmcnt(0)
	v_add_f32_e32 v107, v83, v84
	v_pk_mul_f32 v[102:103], v[106:107], v[108:109]
	v_add_u32_e32 v107, v78, v2
	v_add_f32_e32 v83, v102, v103
	v_div_scale_f32 v84, vcc, v83, v83, 1.0
	v_rcp_f32_e32 v102, v84
	v_ashrrev_i32_e32 v108, 5, v107
	v_ashrrev_i32_e32 v109, 31, v108
	v_lshlrev_b64 v[108:109], 12, v[108:109]
	v_fma_f32 v103, -v84, v102, 1.0
	v_fmac_f32_e32 v102, v103, v102
	v_div_scale_f32 v103, vcc, 1.0, v83, 1.0
	v_mul_f32_e32 v104, v103, v102
	v_fma_f32 v105, -v84, v104, v103
	v_fmac_f32_e32 v104, v105, v102
	v_fma_f32 v84, -v84, v104, v103
	v_div_fmas_f32 v84, v84, v102, v104
	v_or_b32_e32 v102, v2, v59
	v_add_u32_e32 v103, v76, v2
	v_add_u32_e32 v105, v77, v2
	v_ashrrev_i32_e32 v102, 5, v102
	v_ashrrev_i32_e32 v104, 5, v103
	v_ashrrev_i32_e32 v106, 5, v105
	v_ashrrev_i32_e32 v103, 31, v102
	v_ashrrev_i32_e32 v105, 31, v104
	v_ashrrev_i32_e32 v107, 31, v106
	v_lshlrev_b64 v[102:103], 12, v[102:103]
	v_lshlrev_b64 v[104:105], 12, v[104:105]
	v_lshlrev_b64 v[106:107], 12, v[106:107]
	v_lshl_add_u64 v[112:113], v[44:45], 0, v[102:103]
	v_lshl_add_u64 v[122:123], v[46:47], 0, v[104:105]
	v_lshl_add_u64 v[124:125], v[48:49], 0, v[106:107]
	v_lshl_add_u64 v[126:127], v[50:51], 0, v[108:109]
	v_or_b32_e32 v2, v2, v79
	v_ashrrev_i32_e32 v110, 5, v2
	v_ashrrev_i32_e32 v111, 31, v110
	v_lshlrev_b64 v[110:111], 12, v[110:111]
	v_lshl_add_u64 v[128:129], v[52:53], 0, v[110:111]
	global_load_dwordx4 v[102:105], v[112:113], off
	global_load_dwordx4 v[106:109], v[112:113], off offset:1024
	global_load_dwordx4 v[130:133], v[112:113], off offset:2048
	global_load_dwordx4 v[138:141], v[112:113], off offset:3072
	global_load_dwordx4 v[148:151], v[122:123], off
	global_load_dwordx4 v[152:155], v[122:123], off offset:1024
	global_load_dwordx4 v[156:159], v[122:123], off offset:2048
	global_load_dwordx4 v[160:163], v[122:123], off offset:3072
	global_load_dwordx4 v[164:167], v[124:125], off
	global_load_dwordx4 v[168:171], v[124:125], off offset:1024
	global_load_dwordx4 v[172:175], v[124:125], off offset:2048
	global_load_dwordx4 v[176:179], v[124:125], off offset:3072
	global_load_dwordx4 v[180:183], v[126:127], off
	global_load_dwordx4 v[184:187], v[126:127], off offset:1024
	global_load_dwordx4 v[188:191], v[126:127], off offset:2048
	global_load_dwordx4 v[192:195], v[126:127], off offset:3072
	global_load_dwordx4 v[196:199], v[128:129], off
	global_load_dwordx4 v[200:203], v[128:129], off offset:1024
	global_load_dwordx4 v[204:207], v[128:129], off offset:2048
	global_load_dwordx4 v[208:211], v[128:129], off offset:3072
	v_cvt_pk_bf16_f32 v97, v100, v101
	v_cvt_pk_bf16_f32 v86, v86, v88
	v_cvt_pk_bf16_f32 v87, v87, v89
	v_cvt_pk_bf16_f32 v88, v90, v91
	v_cvt_pk_bf16_f32 v89, v92, v93
	v_cvt_pk_bf16_f32 v6, v6, v8
	v_cvt_pk_bf16_f32 v7, v7, v9
	v_cvt_pk_bf16_f32 v8, v15, v16
	v_cvt_pk_bf16_f32 v9, v17, v18
	v_cvt_pk_bf16_f32 v2, v3, v5
	v_cvt_pk_bf16_f32 v3, v4, v10
	v_cvt_pk_bf16_f32 v4, v11, v12
	v_cvt_pk_bf16_f32 v5, v13, v14
	v_cvt_pk_bf16_f32 v118, v19, v21
	v_cvt_pk_bf16_f32 v119, v20, v22
	v_cvt_pk_bf16_f32 v120, v23, v24
	v_cvt_pk_bf16_f32 v121, v25, v85
	s_mov_b64 vcc, 0x15000600
	v_lshl_add_u64 v[56:57], v[56:57], 0, vcc
	s_andn2_b64 vcc, exec, s[2:3]
	s_mov_b64 s[2:3], 0
	s_waitcnt vmcnt(16)
	v_mfma_f32_16x16x32_bf16 v[102:105], v[102:105], v[94:97], 0
	v_mfma_f32_16x16x32_bf16 v[106:109], v[106:109], v[94:97], 0
	v_mfma_f32_16x16x32_bf16 v[130:133], v[130:133], v[94:97], 0
	v_mfma_f32_16x16x32_bf16 v[138:141], v[138:141], v[94:97], 0
	s_waitcnt vmcnt(12)
	v_mfma_f32_16x16x32_bf16 v[102:105], v[148:151], v[86:89], v[102:105]
	v_mfma_f32_16x16x32_bf16 v[106:109], v[152:155], v[86:89], v[106:109]
	v_mfma_f32_16x16x32_bf16 v[130:133], v[156:159], v[86:89], v[130:133]
	v_mfma_f32_16x16x32_bf16 v[138:141], v[160:163], v[86:89], v[138:141]
	s_waitcnt vmcnt(8)
	v_mfma_f32_16x16x32_bf16 v[102:105], v[164:167], v[118:121], v[102:105]
	v_mfma_f32_16x16x32_bf16 v[106:109], v[168:171], v[118:121], v[106:109]
	v_mfma_f32_16x16x32_bf16 v[130:133], v[172:175], v[118:121], v[130:133]
	v_mfma_f32_16x16x32_bf16 v[138:141], v[176:179], v[118:121], v[138:141]
	s_waitcnt vmcnt(4)
	v_mfma_f32_16x16x32_bf16 v[102:105], v[180:183], v[6:9], v[102:105]
	v_mfma_f32_16x16x32_bf16 v[106:109], v[184:187], v[6:9], v[106:109]
	v_mfma_f32_16x16x32_bf16 v[130:133], v[188:191], v[6:9], v[130:133]
	v_mfma_f32_16x16x32_bf16 v[138:141], v[192:195], v[6:9], v[138:141]
	s_waitcnt vmcnt(0)
	v_mfma_f32_16x16x32_bf16 v[10:13], v[196:199], v[2:5], v[102:105]
	v_mfma_f32_16x16x32_bf16 v[14:17], v[200:203], v[2:5], v[106:109]
	v_mfma_f32_16x16x32_bf16 v[18:21], v[204:207], v[2:5], v[130:133]
	v_mfma_f32_16x16x32_bf16 v[86:89], v[208:211], v[2:5], v[138:141]
	s_nop 7
	s_nop 3
	v_pk_fma_f32 v[12:13], v[12:13], v[58:59], v[68:69] op_sel_hi:[1,0,1]
	v_pk_fma_f32 v[14:15], v[14:15], v[58:59], v[62:63] op_sel_hi:[1,0,1]
	v_fma_f32 v22, v10, v58, v60
	v_fma_f32 v23, v11, v58, v61
	s_nop 0
	v_pk_fma_f32 v[8:9], v[16:17], v[58:59], v[70:71] op_sel_hi:[1,0,1]
	v_pk_fma_f32 v[4:5], v[20:21], v[58:59], v[72:73] op_sel_hi:[1,0,1]
	v_pk_fma_f32 v[10:11], v[18:19], v[58:59], v[64:65] op_sel_hi:[1,0,1]
	s_nop 1
	v_pk_fma_f32 v[2:3], v[88:89], v[58:59], v[74:75] op_sel_hi:[1,0,1]
	v_pk_fma_f32 v[6:7], v[86:87], v[58:59], v[66:67] op_sel_hi:[1,0,1]
	v_div_fixup_f32 v16, v84, v83, 1.0
	v_mul_f32_e32 v17, v16, v22
	v_mul_f32_e32 v18, v16, v23
	v_mul_f32_e32 v12, v16, v12
	v_mul_f32_e32 v13, v16, v13
	v_mul_f32_e32 v14, v16, v14
	v_mul_f32_e32 v15, v16, v15
	v_mul_f32_e32 v8, v16, v8
	v_mul_f32_e32 v9, v16, v9
	v_mul_f32_e32 v10, v16, v10
	v_mul_f32_e32 v11, v16, v11
	v_mul_f32_e32 v19, v16, v4
	v_mul_f32_e32 v20, v16, v5
	v_mul_f32_e32 v21, v16, v6
	v_mul_f32_e32 v22, v16, v7
	v_mul_f32_e32 v23, v16, v2
	v_mul_f32_e32 v16, v16, v3
	v_cvt_pk_bf16_f32 v2, v17, v18
	v_cvt_pk_bf16_f32 v3, v12, v13
	v_cvt_pk_bf16_f32 v4, v14, v15
	v_cvt_pk_bf16_f32 v5, v8, v9
	v_cvt_pk_bf16_f32 v6, v10, v11
	v_cvt_pk_bf16_f32 v7, v19, v20
	v_cvt_pk_bf16_f32 v8, v21, v22
	v_cvt_pk_bf16_f32 v9, v23, v16
	flat_store_dwordx2 v[54:55], v[2:3] offset:1536
	flat_store_dwordx2 v[56:57], v[4:5] offset:32
	flat_store_dwordx2 v[56:57], v[6:7] offset:64
	flat_store_dwordx2 v[56:57], v[8:9] offset:96
	s_cbranch_vccz .LBB0_178
	v_readlane_b32 s82, v253, 29
	v_readlane_b32 s48, v255, 57
	v_readlane_b32 s66, v255, 59
	v_readlane_b32 s68, v255, 61
	v_readlane_b32 s70, v255, 63
	v_readlane_b32 s74, v254, 1
	v_readlane_b32 s76, v254, 3
	v_readlane_b32 s78, v254, 5
	v_readlane_b32 s80, v254, 7
	s_mov_b32 s92, 0x2600000
	s_movk_i32 s73, 0x110
	s_mov_b32 s36, 0xf800000
	s_mov_b64 s[34:35], 0xc000
	v_readlane_b32 s83, v253, 30
	s_mov_b32 s97, 0xff800000
	v_readlane_b32 s49, v255, 58
	v_readlane_b32 s67, v255, 60
	v_readlane_b32 s69, v255, 62
	v_readlane_b32 s71, v254, 0
	v_readlane_b32 s75, v254, 2
	v_readlane_b32 s77, v254, 4
	v_readlane_b32 s79, v254, 6
	v_readlane_b32 s81, v254, 8
	v_readlane_b32 s41, v253, 32
	s_branch .LBB0_133
